# fast path v7: + pre-barrier far/near dispatch and read-address calc, next-iteration bookkeeping and K/V prefetch loads interleaved into tile-B PV gaps
# speedup vs baseline: 1.0188x; 1.0050x over previous
; DI void attn_item(const Params& p, int g, int seq, int hd, int qt, int m, char* smem, int split_j, int sub) {
;     ...
;   auto compute = [&](int st, int buf) __attribute__((always_inline)) {
;     const int k0 = (tbase + st) * 32, h = h_, l31 = l31_;
;     const bf16_t* Kb = Ks + buf * 32 * 72; const bf16_t* Vb = Vs + buf * 128 * 40;
;     const int rmin = k0 - (qw0 + 31), rmax = k0 + 31 - qw0;
;     const bool farL = rmax <= -128, farR = rmin >= 128;
;     if (!farL && region == 0) { rescale(__builtin_amdgcn_exp2f(cneg)); region = 1; }
;     if (farR && region == 1) { rescale(__builtin_amdgcn_exp2f(-cpos)); region = 2; }
;     bf16x8 kf[4], vf[2][4];
; #pragma unroll
;     for (int s = 0; s < 4; ++s) kf[s] = *(const bf16x8*)(Kb + l31 * 72 + s * 16 + h * 8);
; #pragma unroll
;     for (int s2 = 0; s2 < 2; ++s2)
; #pragma unroll
;       for (int dt = 0; dt < 4; ++dt) vf[s2][dt] = *(const bf16x8*)(Vb + (dt * 32 + l31) * 40 + s2 * 16 + h * 8);
;     __builtin_amdgcn_sched_barrier(0);
;     f32x16 X;
; #pragma unroll
;     for (int r = 0; r < 16; ++r) X[r] = 0.f;
; #pragma unroll
;     for (int s = 0; s < 4; ++s) X = MFMA32(kf[s], qf[s], X);
;     if (farL || farR) {
; #pragma unroll
;       for (int r = 0; r < 16; ++r) X[r] = __builtin_amdgcn_exp2f(X[r]);
;     } else {
;       const int rel0 = k0 - (qw0 + l31) + 128;
; #pragma unroll
;       for (int r = 0; r < 16; ++r) { int idx = rel0 + crow(r, h); idx = idx < 0 ? 0 : (idx > 256 ? 256 : idx); X[r] = __builtin_amdgcn_exp2f(X[r] + tab[idx]); }
;     }
;     bf16x8 pf[2];
; #pragma unroll
;     for (int s2 = 0; s2 < 2; ++s2) {
;       u32x4 w; w.x = pk_bf16(X[8 * s2], X[8 * s2 + 1]); w.y = pk_bf16(X[8 * s2 + 2], X[8 * s2 + 3]); w.z = pk_bf16(X[8 * s2 + 4], X[8 * s2 + 5]); w.w = pk_bf16(X[8 * s2 + 6], X[8 * s2 + 7]);
;       ls2 += (f32x2){X[8 * s2], X[8 * s2 + 1]}; ls2 += (f32x2){X[8 * s2 + 2], X[8 * s2 + 3]};
;       ls2 += (f32x2){X[8 * s2 + 4], X[8 * s2 + 5]}; ls2 += (f32x2){X[8 * s2 + 6], X[8 * s2 + 7]};
;       pf[s2] = __builtin_bit_cast(bf16x8, w);
;     }
; #pragma unroll
;     for (int s2 = 0; s2 < 2; ++s2)
; #pragma unroll
;       for (int dt = 0; dt < 4; ++dt) O[dt] = MFMA32(pf[s2], vf[s2][dt], O[dt]);
;   };
;   load_tile(0, rkA, rvA0, rvA1);
;   load_tile(1, rkB, rvB0, rvB1);
;   __syncthreads();
;   store_tile(0, rkA, rvA0, rvA1);
;   store_tile(1, rkB, rvB0, rvB1);
;   __syncthreads();
.Lat2_reads:
	ds_read_b128 v[64:67], v192
	ds_read_b128 v[80:83], v192 offset:32
	ds_read_b128 v[84:87], v192 offset:64
	ds_read_b128 v[88:91], v192 offset:96
	ds_read_b128 v[220:223], v192 offset:4608
	ds_read_b128 v[224:227], v192 offset:4640
	ds_read_b128 v[236:239], v192 offset:4672
	ds_read_b128 v[240:243], v192 offset:4704
	ds_read_b128 v[156:159], v244 offset:18432
	ds_read_b128 v[160:163], v244 offset:20992
	ds_read_b128 v[164:167], v244 offset:23552
	ds_read_b128 v[152:155], v244 offset:26112
	s_waitcnt lgkmcnt(11)
	v_mfma_f32_32x32x16_bf16 v[64:79], v[64:67], v[104:107], 0
	s_waitcnt lgkmcnt(10)
	v_mfma_f32_32x32x16_bf16 v[64:79], v[80:83], v[108:111], v[64:79]
	s_waitcnt lgkmcnt(9)
	v_mfma_f32_32x32x16_bf16 v[64:79], v[84:87], v[112:115], v[64:79]
	s_waitcnt lgkmcnt(8)
	v_mfma_f32_32x32x16_bf16 v[64:79], v[88:91], v[116:119], v[64:79]
	ds_read_b128 v[148:151], v244 offset:18464
	ds_read_b128 v[144:147], v244 offset:21024
	ds_read_b128 v[136:139], v244 offset:23584
	ds_read_b128 v[140:143], v244 offset:26144
	s_waitcnt lgkmcnt(11)
	v_mfma_f32_32x32x16_bf16 v[80:95], v[220:223], v[104:107], 0
	s_waitcnt lgkmcnt(10)
	v_mfma_f32_32x32x16_bf16 v[80:95], v[224:227], v[108:111], v[80:95]
	v_exp_f32_e32 v64, v64
	v_exp_f32_e32 v65, v65
	v_exp_f32_e32 v66, v66
	v_exp_f32_e32 v67, v67
	v_exp_f32_e32 v68, v68
	v_exp_f32_e32 v69, v69
	s_waitcnt lgkmcnt(9)
	v_mfma_f32_32x32x16_bf16 v[80:95], v[236:239], v[112:115], v[80:95]
	v_exp_f32_e32 v70, v70
	v_exp_f32_e32 v71, v71
	v_exp_f32_e32 v72, v72
	v_exp_f32_e32 v73, v73
	v_exp_f32_e32 v74, v74
	v_exp_f32_e32 v75, v75
	s_waitcnt lgkmcnt(8)
	v_mfma_f32_32x32x16_bf16 v[80:95], v[240:243], v[116:119], v[80:95]
	v_exp_f32_e32 v76, v76
	v_exp_f32_e32 v77, v77
	v_exp_f32_e32 v78, v78
	v_exp_f32_e32 v79, v79
	v_cvt_pk_bf16_f32 v220, v64, v65
	v_cvt_pk_bf16_f32 v221, v66, v67
	v_cvt_pk_bf16_f32 v222, v68, v69
	v_cvt_pk_bf16_f32 v223, v70, v71
	v_cvt_pk_bf16_f32 v224, v72, v73
	v_cvt_pk_bf16_f32 v225, v74, v75
	v_cvt_pk_bf16_f32 v226, v76, v77
	v_cvt_pk_bf16_f32 v227, v78, v79
	s_waitcnt lgkmcnt(7)
	v_mfma_f32_32x32x16_bf16 v[48:63], v[220:223], v[156:159], v[48:63]
	ds_read_b128 v[156:159], v244 offset:28672
	v_exp_f32_e32 v80, v80
	v_exp_f32_e32 v81, v81
	v_exp_f32_e32 v82, v82
	s_waitcnt lgkmcnt(7)
	v_mfma_f32_32x32x16_bf16 v[32:47], v[220:223], v[160:163], v[32:47]
	ds_read_b128 v[160:163], v244 offset:31232
	v_exp_f32_e32 v83, v83
	v_exp_f32_e32 v84, v84
	v_exp_f32_e32 v85, v85
	s_waitcnt lgkmcnt(7)
	v_mfma_f32_32x32x16_bf16 v[16:31], v[220:223], v[164:167], v[16:31]
	ds_read_b128 v[164:167], v244 offset:33792
	v_exp_f32_e32 v86, v86
	v_exp_f32_e32 v87, v87
	v_exp_f32_e32 v88, v88
	s_waitcnt lgkmcnt(7)
	v_mfma_f32_32x32x16_bf16 v[0:15], v[220:223], v[152:155], v[0:15]
	ds_read_b128 v[152:155], v244 offset:36352
	v_exp_f32_e32 v89, v89
	v_exp_f32_e32 v90, v90
	v_exp_f32_e32 v91, v91
	s_waitcnt lgkmcnt(7)
	v_mfma_f32_32x32x16_bf16 v[48:63], v[224:227], v[148:151], v[48:63]
	ds_read_b128 v[148:151], v244 offset:28704
	v_exp_f32_e32 v92, v92
	v_exp_f32_e32 v93, v93
	v_exp_f32_e32 v94, v94
	v_exp_f32_e32 v95, v95
	s_waitcnt lgkmcnt(7)
	v_mfma_f32_32x32x16_bf16 v[32:47], v[224:227], v[144:147], v[32:47]
	ds_read_b128 v[144:147], v244 offset:31264
	v_cvt_pk_bf16_f32 v236, v80, v81
	v_cvt_pk_bf16_f32 v237, v82, v83
	v_cvt_pk_bf16_f32 v238, v84, v85
	s_waitcnt lgkmcnt(7)
	v_mfma_f32_32x32x16_bf16 v[16:31], v[224:227], v[136:139], v[16:31]
	ds_read_b128 v[136:139], v244 offset:33824
	v_cvt_pk_bf16_f32 v239, v86, v87
	v_cvt_pk_bf16_f32 v240, v88, v89
	v_cvt_pk_bf16_f32 v241, v90, v91
	s_waitcnt lgkmcnt(7)
	v_mfma_f32_32x32x16_bf16 v[0:15], v[224:227], v[140:143], v[0:15]
	ds_read_b128 v[140:143], v244 offset:36384
	v_cvt_pk_bf16_f32 v242, v92, v93
	v_cvt_pk_bf16_f32 v243, v94, v95
	s_andn2_b64 vcc, exec, s[8:9]
	s_cbranch_vccnz .Lat2_pvplain
	s_add_i32 s10, s15, 1
	s_cmp_lt_u32 s10, s73
	s_cbranch_scc0 .Lat2_pvw
	s_xor_b32 s7, s16, 2
	s_mul_i32 s8, s7, 0x2800
	s_add_i32 s8, s8, 32
	s_mulk_i32 s7, 0x1200
	v_add_u32_e32 v192, s7, v169
	v_add3_u32 v244, s8, v189, v190
	s_addk_i32 s8, 0x2800
	s_add_i32 s13, s13, 64
	s_add_i32 s6, s6, 2
	s_mov_b32 s15, s10
	s_mov_b64 s[20:21], 0x1000
	s_waitcnt lgkmcnt(7)
	v_mfma_f32_32x32x16_bf16 v[48:63], v[236:239], v[156:159], v[48:63]
	s_waitcnt vmcnt(5)
	ds_write_b128 v192, v[96:99]
	s_add_i32 s50, s6, -1
	s_lshl_b64 s[10:11], s[50:51], 12
	v_lshl_add_u64 v[220:221], v[172:173], 0, s[10:11]
	v_pk_add_f32 v[246:247], v[66:67], v[70:71]
	v_pk_add_f32 v[186:187], v[186:187], v[64:65]
	s_waitcnt lgkmcnt(7)
	v_mfma_f32_32x32x16_bf16 v[32:47], v[236:239], v[160:163], v[32:47]
	s_waitcnt vmcnt(4)
	ds_write_b128 v244, v[100:103] offset:18432
	global_load_dwordx4 v[96:99], v[220:221], off
	s_lshl_b64 s[10:11], s[50:51], 13
	v_lshl_add_u64 v[222:223], v[170:171], 0, s[10:11]
	v_pk_add_f32 v[246:247], v[246:247], v[74:75]
	v_pk_add_f32 v[186:187], v[186:187], v[68:69]
	s_waitcnt lgkmcnt(7)
	v_mfma_f32_32x32x16_bf16 v[16:31], v[236:239], v[164:167], v[16:31]
	s_waitcnt vmcnt(4)
	ds_write_b128 v244, v[120:123] offset:23552
	global_load_dwordx4 v[100:103], v[222:223], off
	v_lshl_add_u64 v[224:225], v[222:223], 0, s[20:21]
	v_pk_add_f32 v[246:247], v[246:247], v[78:79]
	v_pk_add_f32 v[186:187], v[186:187], v[72:73]
	s_waitcnt lgkmcnt(7)
	v_mfma_f32_32x32x16_bf16 v[0:15], v[236:239], v[152:155], v[0:15]
	s_waitcnt vmcnt(4)
	ds_write_b128 v192, v[124:127] offset:4608
	global_load_dwordx4 v[120:123], v[224:225], off
	s_mov_b32 s7, s51
	s_lshl_b64 s[10:11], s[6:7], 12
	v_lshl_add_u64 v[220:221], v[172:173], 0, s[10:11]
	v_pk_add_f32 v[186:187], v[186:187], v[76:77]
	v_pk_add_f32 v[186:187], v[186:187], v[246:247]
	s_waitcnt lgkmcnt(7)
	v_mfma_f32_32x32x16_bf16 v[48:63], v[240:243], v[148:151], v[48:63]
	v_add3_u32 v192, s8, v189, v190
	s_waitcnt vmcnt(4)
	ds_write_b128 v192, v[128:131] offset:18432
	global_load_dwordx4 v[124:127], v[220:221], off
	s_lshl_b64 s[10:11], s[6:7], 13
	v_lshl_add_u64 v[222:223], v[170:171], 0, s[10:11]
	v_pk_add_f32 v[246:247], v[82:83], v[86:87]
	v_pk_add_f32 v[186:187], v[186:187], v[80:81]
	s_waitcnt lgkmcnt(7)
	v_mfma_f32_32x32x16_bf16 v[32:47], v[240:243], v[144:147], v[32:47]
	s_waitcnt vmcnt(4)
	ds_write_b128 v192, v[132:135] offset:23552
	global_load_dwordx4 v[128:131], v[222:223], off
	v_lshl_add_u64 v[224:225], v[222:223], 0, s[20:21]
	v_pk_add_f32 v[246:247], v[246:247], v[90:91]
	v_pk_add_f32 v[186:187], v[186:187], v[84:85]
	s_waitcnt lgkmcnt(7)
	v_mfma_f32_32x32x16_bf16 v[16:31], v[240:243], v[136:139], v[16:31]
	global_load_dwordx4 v[132:135], v[224:225], off
	v_pk_add_f32 v[246:247], v[246:247], v[94:95]
	v_pk_add_f32 v[186:187], v[186:187], v[88:89]
	s_waitcnt lgkmcnt(6)
	v_mfma_f32_32x32x16_bf16 v[0:15], v[240:243], v[140:143], v[0:15]
	v_pk_add_f32 v[186:187], v[186:187], v[92:93]
	v_pk_add_f32 v[186:187], v[186:187], v[246:247]
	s_mov_b64 s[8:9], -1
	s_branch .Lat2_nopf
; DI void attn_item(const Params& p, int g, int seq, int hd, int qt, int m, char* smem, int split_j, int sub) {
;     ...
;   for (int it = 0; it < npairs; ++it) {
;     const int set = it & 1;
;     if (it + 1 < npairs) { load_tile(2 * it + 2, rkA, rvA0, rvA1); load_tile(2 * it + 3, rkB, rvB0, rvB1); }
;     compute(2 * it, 2 * set);
;     compute(2 * it + 1, 2 * set + 1);
;     if (it + 1 < npairs) { store_tile(2 * (set ^ 1), rkA, rvA0, rvA1); store_tile(2 * (set ^ 1) + 1, rkB, rvB0, rvB1); }
.Lat2_pvw:
	s_xor_b32 s7, s16, 2
	s_mul_i32 s8, s7, 0x2800
	s_add_i32 s8, s8, 32
	s_mulk_i32 s7, 0x1200
	v_add_u32_e32 v192, s7, v169
	v_add3_u32 v244, s8, v189, v190
	s_addk_i32 s8, 0x2800
	s_waitcnt lgkmcnt(7)
	v_mfma_f32_32x32x16_bf16 v[48:63], v[236:239], v[156:159], v[48:63]
	s_waitcnt vmcnt(5)
	ds_write_b128 v192, v[96:99]
	v_pk_add_f32 v[246:247], v[66:67], v[70:71]
	v_pk_add_f32 v[186:187], v[186:187], v[64:65]
	s_waitcnt lgkmcnt(7)
	v_mfma_f32_32x32x16_bf16 v[32:47], v[236:239], v[160:163], v[32:47]
	s_waitcnt vmcnt(4)
	ds_write_b128 v244, v[100:103] offset:18432
	v_pk_add_f32 v[246:247], v[246:247], v[74:75]
	v_pk_add_f32 v[186:187], v[186:187], v[68:69]
	s_waitcnt lgkmcnt(7)
	v_mfma_f32_32x32x16_bf16 v[16:31], v[236:239], v[164:167], v[16:31]
	s_waitcnt vmcnt(3)
	ds_write_b128 v244, v[120:123] offset:23552
	v_pk_add_f32 v[246:247], v[246:247], v[78:79]
	v_pk_add_f32 v[186:187], v[186:187], v[72:73]
	s_waitcnt lgkmcnt(7)
	v_mfma_f32_32x32x16_bf16 v[0:15], v[236:239], v[152:155], v[0:15]
	s_waitcnt vmcnt(2)
	ds_write_b128 v192, v[124:127] offset:4608
	v_pk_add_f32 v[186:187], v[186:187], v[76:77]
	v_pk_add_f32 v[186:187], v[186:187], v[246:247]
	s_waitcnt lgkmcnt(7)
	v_mfma_f32_32x32x16_bf16 v[48:63], v[240:243], v[148:151], v[48:63]
	v_add3_u32 v192, s8, v189, v190
	s_waitcnt vmcnt(1)
	ds_write_b128 v192, v[128:131] offset:18432
	v_pk_add_f32 v[246:247], v[82:83], v[86:87]
	v_pk_add_f32 v[186:187], v[186:187], v[80:81]
	s_waitcnt lgkmcnt(7)
	v_mfma_f32_32x32x16_bf16 v[32:47], v[240:243], v[144:147], v[32:47]
	s_waitcnt vmcnt(0)
	ds_write_b128 v192, v[132:135] offset:23552
	v_pk_add_f32 v[246:247], v[246:247], v[90:91]
	v_pk_add_f32 v[186:187], v[186:187], v[84:85]
	s_waitcnt lgkmcnt(7)
	v_mfma_f32_32x32x16_bf16 v[16:31], v[240:243], v[136:139], v[16:31]
	v_pk_add_f32 v[246:247], v[246:247], v[94:95]
	v_pk_add_f32 v[186:187], v[186:187], v[88:89]
	s_waitcnt lgkmcnt(6)
	v_mfma_f32_32x32x16_bf16 v[0:15], v[240:243], v[140:143], v[0:15]
	v_pk_add_f32 v[186:187], v[186:187], v[92:93]
	v_pk_add_f32 v[186:187], v[186:187], v[246:247]
	s_branch .Lat2_bot

; DI void attn_item(const Params& p, int g, int seq, int hd, int qt, int m, char* smem, int split_j, int sub) {
;     ...
;     const int k0 = (tbase + st) * 32, h = h_, l31 = l31_;
;     const bf16_t* Kb = Ks + buf * 32 * 72; const bf16_t* Vb = Vs + buf * 128 * 40;
;     const int rmin = k0 - (qw0 + 31), rmax = k0 + 31 - qw0;
;     const bool farL = rmax <= -128, farR = rmin >= 128;
;     if (!farL && region == 0) { rescale(__builtin_amdgcn_exp2f(cneg)); region = 1; }
;     if (farR && region == 1) { rescale(__builtin_amdgcn_exp2f(-cpos)); region = 2; }
;     ...
;   for (int it = 0; it < npairs; ++it) {
;     const int set = it & 1;
;     if (it + 1 < npairs) { load_tile(2 * it + 2, rkA, rvA0, rvA1); load_tile(2 * it + 3, rkB, rvB0, rvB1); }
;     compute(2 * it, 2 * set);
;     compute(2 * it + 1, 2 * set + 1);
;     if (it + 1 < npairs) { store_tile(2 * (set ^ 1), rkA, rvA0, rvA1); store_tile(2 * (set ^ 1) + 1, rkB, rvB0, rvB1); }
;     __syncthreads();
.Lat2_bot:
	s_add_i32 s13, s13, 64
	s_add_i32 s6, s6, 2
	s_cmp_lg_u32 s73, s15
	s_cbranch_scc0 .Lat2_exit
	s_add_i32 s15, s15, 1
	s_cmp_lt_u32 s15, s73
	s_cselect_b64 s[8:9], -1, 0
	s_cmp_ge_u32 s15, s73
	s_cbranch_scc1 .Lat2_nopf
	s_add_i32 s50, s6, -1
	s_lshl_b64 s[10:11], s[50:51], 12
	v_lshl_add_u64 v[220:221], v[172:173], 0, s[10:11]
	s_lshl_b64 s[10:11], s[50:51], 13
	v_lshl_add_u64 v[222:223], v[170:171], 0, s[10:11]
	s_mov_b32 s7, s51
	global_load_dwordx4 v[96:99], v[220:221], off
	global_load_dwordx4 v[100:103], v[222:223], off
	v_add_co_u32_e32 v220, vcc, 0x1000, v222
	s_lshl_b64 s[10:11], s[6:7], 12
	s_nop 0
	v_addc_co_u32_e32 v221, vcc, 0, v223, vcc
	v_lshl_add_u64 v[222:223], v[172:173], 0, s[10:11]
	s_lshl_b64 s[10:11], s[6:7], 13
	global_load_dwordx4 v[120:123], v[220:221], off
	global_load_dwordx4 v[124:127], v[222:223], off
	v_lshl_add_u64 v[220:221], v[170:171], 0, s[10:11]
	v_add_co_u32_e32 v222, vcc, 0x1000, v220
	s_nop 1
	v_addc_co_u32_e32 v223, vcc, 0, v221, vcc
	global_load_dwordx4 v[128:131], v[220:221], off
	global_load_dwordx4 v[132:135], v[222:223], off
.Lat2_nopf:
	s_add_i32 s7, s14, s13
	s_cmpk_lt_i32 s7, 0xff42
	s_cbranch_scc1 .Lat2_far
	s_cmpk_gt_i32 s7, 0x9e
	s_cbranch_scc0 .Lat2_near
	s_cmp_eq_u32 s17, 2
	s_cbranch_scc1 .Lat2_far
.Lat2_near:
	s_waitcnt lgkmcnt(0)
	s_barrier
	s_branch .LBB0_319
.Lat2_far:
	s_add_i32 s10, s6, -3
	s_and_b32 s16, s10, 2
	s_mul_i32 s10, s16, 0x1200
	s_mul_i32 s18, s16, 0x2800
	v_add_u32_e32 v192, s10, v191
	v_add_u32_e32 v244, s18, v196
	s_waitcnt lgkmcnt(0)
	s_barrier
	s_branch .Lat2_reads
